# residual epilogues (P5, P7): the per-row-group sum-of-squares float atomics are issued in one burst at the end of the epilogue instead of between row groups (in-order vmcnt waits no longer queue behin
# speedup vs baseline: 1.0131x; 1.0030x over previous
; __device__ __forceinline__ unsigned cvt_pk_bf16(float lo, float hi) { unsigned r; asm volatile("v_cvt_pk_bf16_f32 %0, %1, %2" : "=v"(r) : "v"(lo), "v"(hi)); return r; }
; #define UNPK4(q, lo, hi) const f32x4 lo = (f32x4){bf_lo((q).x), bf_hi((q).x), bf_lo((q).y), bf_hi((q).y)}, hi = (f32x4){bf_lo((q).z), bf_hi((q).z), bf_lo((q).w), bf_hi((q).w)}
;     __device__ __forceinline__ void operator()(EPI_ARGS) const {
;         const int col0 = u.pn * 256 + wc * 32 + 8 * fq;
;         float nr[8];
; #pragma unroll
;         for (int g = 0; g < 8; ++g) nr[g] = nrm[ROW_OF(g >> 2, g & 3)];
;         u32x4 xc[2], xq[2];
; #pragma unroll
;         for (int bj = 0; bj < 2; ++bj) xc[bj] = *(const u32x4*)(xn + (size_t)ROW_OF(0, 0) * D + col0 + bj * 128);
; #pragma unroll
;         for (int g = 0; g < 8; ++g) {
;             const int ai = g >> 2, m = g & 3, row = ROW_OF(ai, m); float s = 0.f;
;             if (g < 7) {
; #pragma unroll
;                 for (int bj = 0; bj < 2; ++bj) xq[bj] = *(const u32x4*)(xn + (size_t)ROW_OF((g + 1) >> 2, (g + 1) & 3) * D + col0 + bj * 128);
;             }
; #pragma unroll
;             for (int bj = 0; bj < 2; ++bj) {
;                 const size_t off = (size_t)row * D + col0 + bj * 128;
;                 UNPK4(xc[bj], x0, x1);
;                 const f32x4 v0 = x0 * nr[g] + acc[ai][bj][m][0], v1 = x1 * nr[g] + acc[ai][bj][m][1];
;                 s += (v0[0] * v0[0] + v0[1] * v0[1]) + (v0[2] * v0[2] + v0[3] * v0[3]) + (v1[0] * v1[0] + v1[1] * v1[1]) + (v1[2] * v1[2] + v1[3] * v1[3]);
;                 u32x4 w; w.x = cvt_pk_bf16(v0[0], v0[1]); w.y = cvt_pk_bf16(v0[2], v0[3]); w.z = cvt_pk_bf16(v1[0], v1[1]); w.w = cvt_pk_bf16(v1[2], v1[3]); *(u32x4*)(xb + off) = w;
;             }
;             s += __shfl_xor(s, 16); s += __shfl_xor(s, 32);
;             if (fq == 0) __hip_atomic_fetch_add(ss + row, s, __ATOMIC_RELAXED, __HIP_MEMORY_SCOPE_AGENT);
;             if (g < 7) { xc[0] = xq[0]; xc[1] = xq[1]; }
;         }
;     }
.LBB0_832:
	s_lshl_b32 s12, s58, 8
	v_mov_b32_e32 v128, v159
	v_mov_b32_e32 v176, v163
	s_add_i32 s12, s12, s23
	v_xor_b32_e32 v177, 16, v213
	v_add_u32_e32 v160, s12, v128
	s_lshl_b32 s12, s56, 8
	s_or_b32 s12, s12, s24
	v_ashrrev_i32_e32 v161, 31, v160
	v_lshl_add_u32 v152, v176, 3, s12
	v_lshlrev_b64 v[186:187], 12, v[160:161]
	v_ashrrev_i32_e32 v153, 31, v152
	v_lshl_add_u64 v[128:129], s[40:41], 0, v[186:187]
	v_lshlrev_b64 v[156:157], 1, v[152:153]
	v_lshl_add_u64 v[128:129], v[128:129], 0, v[156:157]
	global_load_dwordx4 v[178:181], v[128:129], off
	global_load_dwordx4 v[182:185], v[128:129], off offset:256
	v_lshl_add_u64 v[128:129], v[160:161], 2, s[94:95]
	global_load_dword v188, v[128:129], off
	v_add_u32_e32 v170, 16, v160
	global_load_dword v174, v[128:129], off offset:64
	global_load_dword v168, v[128:129], off offset:128
	global_load_dword v166, v[128:129], off offset:192
	global_load_dword v164, v[128:129], off offset:512
	global_load_dword v162, v[128:129], off offset:576
	global_load_dword v158, v[128:129], off offset:640
	global_load_dword v154, v[128:129], off offset:704
	v_ashrrev_i32_e32 v171, 31, v170
	v_lshlrev_b64 v[172:173], 12, v[170:171]
	v_lshl_add_u64 v[128:129], s[40:41], 0, v[172:173]
	v_lshl_add_u64 v[128:129], v[128:129], 0, v[156:157]
	global_load_dwordx4 v[132:135], v[128:129], off
	s_nop 0
	global_load_dwordx4 v[128:131], v[128:129], off offset:256
	v_add_u32_e32 v189, 64, v214
	v_xor_b32_e32 v190, 32, v213
	v_cmp_lt_i32_e32 vcc, v177, v189
	v_lshl_add_u64 v[186:187], s[2:3], 0, v[186:187]
	v_lshl_add_u64 v[186:187], v[186:187], 0, v[156:157]
	v_cndmask_b32_e32 v177, v213, v177, vcc
	v_cmp_lt_i32_e32 vcc, v190, v189
	s_waitcnt vmcnt(0)
	v_and_b32_e32 v191, 0xffff0000, v178
	v_cndmask_b32_e32 v189, v213, v190, vcc
	v_lshlrev_b32_e32 v190, 16, v178
	v_lshlrev_b32_e32 v178, 16, v179
	v_and_b32_e32 v179, 0xffff0000, v179
	v_lshlrev_b32_e32 v194, 16, v182
	v_and_b32_e32 v195, 0xffff0000, v182
	v_lshlrev_b32_e32 v182, 16, v183
	v_and_b32_e32 v183, 0xffff0000, v183
	v_lshlrev_b32_e32 v192, 16, v180
	v_and_b32_e32 v193, 0xffff0000, v180
	v_lshlrev_b32_e32 v180, 16, v181
	v_and_b32_e32 v181, 0xffff0000, v181
	v_lshlrev_b32_e32 v196, 16, v184
	v_and_b32_e32 v197, 0xffff0000, v184
	v_lshlrev_b32_e32 v184, 16, v185
	v_and_b32_e32 v185, 0xffff0000, v185
	v_pk_fma_f32 v[126:127], v[188:189], v[178:179], v[126:127] op_sel_hi:[0,1,1]
	v_pk_fma_f32 v[124:125], v[188:189], v[190:191], v[124:125] op_sel_hi:[0,1,1]
	v_pk_fma_f32 v[118:119], v[188:189], v[182:183], v[118:119] op_sel_hi:[0,1,1]
	v_pk_fma_f32 v[116:117], v[188:189], v[194:195], v[116:117] op_sel_hi:[0,1,1]
	v_pk_fma_f32 v[122:123], v[188:189], v[180:181], v[122:123] op_sel_hi:[0,1,1]
	v_pk_fma_f32 v[120:121], v[188:189], v[192:193], v[120:121] op_sel_hi:[0,1,1]
	v_pk_fma_f32 v[178:179], v[188:189], v[184:185], v[114:115] op_sel_hi:[0,1,1]
	v_pk_fma_f32 v[180:181], v[188:189], v[196:197], v[112:113] op_sel_hi:[0,1,1]
	v_mul_f32_e32 v114, v125, v125
	v_mul_f32_e32 v115, v127, v127
	v_cvt_pk_bf16_f32 v112, v124, v125
	v_cvt_pk_bf16_f32 v113, v126, v127
	v_mul_f32_e32 v125, v117, v117
	v_mul_f32_e32 v127, v119, v119
	v_cmp_eq_u32_e32 vcc, 0, v176
	v_lshlrev_b32_e32 v176, 2, v177
	v_mul_f32_e32 v177, v121, v121
	v_mul_f32_e32 v183, v181, v181
	v_fmac_f32_e32 v114, v124, v124
	v_fmac_f32_e32 v115, v126, v126
	v_fmac_f32_e32 v125, v116, v116
	v_fmac_f32_e32 v127, v118, v118
	v_mul_f32_e32 v182, v123, v123
	v_mul_f32_e32 v184, v179, v179
	v_fmac_f32_e32 v177, v120, v120
	v_fmac_f32_e32 v183, v180, v180
	v_add_f32_e32 v114, v114, v115
	v_add_f32_e32 v115, v125, v127
	v_fmac_f32_e32 v182, v122, v122
	v_fmac_f32_e32 v184, v178, v178
	v_add_f32_e32 v114, v177, v114
	v_add_f32_e32 v115, v183, v115
	v_add_f32_e32 v114, v182, v114
	v_add_f32_e32 v115, v184, v115
	v_add_f32_e32 v124, v114, v115
	ds_bpermute_b32 v125, v176, v124
	v_cvt_pk_bf16_f32 v114, v120, v121
	v_cvt_pk_bf16_f32 v115, v122, v123
	global_store_dwordx4 v[186:187], v[112:115], off
	s_waitcnt lgkmcnt(0)
	s_nop 0
	v_add_f32_e32 v112, v124, v125
	v_lshlrev_b32_e32 v124, 2, v189
	ds_bpermute_b32 v113, v124, v112
	v_cvt_pk_bf16_f32 v114, v116, v117
	v_cvt_pk_bf16_f32 v115, v118, v119
	v_cvt_pk_bf16_f32 v116, v180, v181
	v_cvt_pk_bf16_f32 v117, v178, v179
	global_store_dwordx4 v[186:187], v[114:117], off offset:256
	s_and_saveexec_b64 s[12:13], vcc
	s_cbranch_execz .LBB0_834
	v_lshl_add_u64 v[114:115], v[160:161], 2, s[68:69]
	s_waitcnt lgkmcnt(0)
	v_add_f32_e32 v112, v112, v113
	v_mov_b32_e32 v236, v112
; __device__ __forceinline__ unsigned cvt_pk_bf16(float lo, float hi) { unsigned r; asm volatile("v_cvt_pk_bf16_f32 %0, %1, %2" : "=v"(r) : "v"(lo), "v"(hi)); return r; }
; #define UNPK4(q, lo, hi) const f32x4 lo = (f32x4){bf_lo((q).x), bf_hi((q).x), bf_lo((q).y), bf_hi((q).y)}, hi = (f32x4){bf_lo((q).z), bf_hi((q).z), bf_lo((q).w), bf_hi((q).w)}
;     __device__ __forceinline__ void operator()(EPI_ARGS) const {
;     ...
;         for (int g = 0; g < 8; ++g) {
;             const int ai = g >> 2, m = g & 3, row = ROW_OF(ai, m); float s = 0.f;
;             if (g < 7) {
; #pragma unroll
;                 for (int bj = 0; bj < 2; ++bj) xq[bj] = *(const u32x4*)(xn + (size_t)ROW_OF((g + 1) >> 2, (g + 1) & 3) * D + col0 + bj * 128);
;             }
; #pragma unroll
;             for (int bj = 0; bj < 2; ++bj) {
;                 const size_t off = (size_t)row * D + col0 + bj * 128;
;                 UNPK4(xc[bj], x0, x1);
;                 const f32x4 v0 = x0 * nr[g] + acc[ai][bj][m][0], v1 = x1 * nr[g] + acc[ai][bj][m][1];
;                 s += (v0[0] * v0[0] + v0[1] * v0[1]) + (v0[2] * v0[2] + v0[3] * v0[3]) + (v1[0] * v1[0] + v1[1] * v1[1]) + (v1[2] * v1[2] + v1[3] * v1[3]);
;                 u32x4 w; w.x = cvt_pk_bf16(v0[0], v0[1]); w.y = cvt_pk_bf16(v0[2], v0[3]); w.z = cvt_pk_bf16(v1[0], v1[1]); w.w = cvt_pk_bf16(v1[2], v1[3]); *(u32x4*)(xb + off) = w;
;             }
;             s += __shfl_xor(s, 16); s += __shfl_xor(s, 32);
;             if (fq == 0) __hip_atomic_fetch_add(ss + row, s, __ATOMIC_RELAXED, __HIP_MEMORY_SCOPE_AGENT);
;             if (g < 7) { xc[0] = xq[0]; xc[1] = xq[1]; }
;         }
.LBB0_834:
	s_or_b64 exec, exec, s[12:13]
	v_add_u32_e32 v120, 32, v160
	v_ashrrev_i32_e32 v121, 31, v120
	v_lshlrev_b64 v[122:123], 12, v[120:121]
	s_waitcnt lgkmcnt(0)
	v_lshl_add_u64 v[112:113], s[40:41], 0, v[122:123]
	v_lshl_add_u64 v[112:113], v[112:113], 0, v[156:157]
	global_load_dwordx4 v[116:119], v[112:113], off
	s_nop 0
	global_load_dwordx4 v[112:115], v[112:113], off offset:256
	v_lshlrev_b32_e32 v126, 16, v132
	v_and_b32_e32 v127, 0xffff0000, v132
	v_lshlrev_b32_e32 v132, 16, v133
	v_and_b32_e32 v133, 0xffff0000, v133
	v_lshlrev_b32_e32 v178, 16, v134
	v_and_b32_e32 v179, 0xffff0000, v134
	v_lshlrev_b32_e32 v134, 16, v135
	v_and_b32_e32 v135, 0xffff0000, v135
	v_pk_fma_f32 v[110:111], v[174:175], v[132:133], v[110:111] op_sel_hi:[0,1,1]
	v_pk_fma_f32 v[108:109], v[174:175], v[126:127], v[108:109] op_sel_hi:[0,1,1]
	v_pk_fma_f32 v[126:127], v[174:175], v[134:135], v[106:107] op_sel_hi:[0,1,1]
	v_pk_fma_f32 v[106:107], v[174:175], v[178:179], v[104:105] op_sel_hi:[0,1,1]
	v_mul_f32_e32 v104, v109, v109
	v_mul_f32_e32 v105, v111, v111
	v_fmac_f32_e32 v104, v108, v108
	v_fmac_f32_e32 v105, v110, v110
	v_add_f32_e32 v104, v104, v105
	v_mul_f32_e32 v105, v107, v107
	v_fmac_f32_e32 v105, v106, v106
	v_add_f32_e32 v104, v105, v104
	v_mul_f32_e32 v105, v127, v127
	v_fmac_f32_e32 v105, v126, v126
	v_add_f32_e32 v125, v105, v104
	v_cvt_pk_bf16_f32 v104, v108, v109
	v_cvt_pk_bf16_f32 v105, v110, v111
	v_lshlrev_b32_e32 v108, 16, v128
	v_and_b32_e32 v109, 0xffff0000, v128
	v_lshlrev_b32_e32 v110, 16, v129
	v_and_b32_e32 v111, 0xffff0000, v129
	v_cvt_pk_bf16_f32 v106, v106, v107
	v_cvt_pk_bf16_f32 v107, v126, v127
	v_lshlrev_b32_e32 v126, 16, v130
	v_and_b32_e32 v127, 0xffff0000, v130
	v_pk_fma_f32 v[102:103], v[174:175], v[110:111], v[102:103] op_sel_hi:[0,1,1]
	v_pk_fma_f32 v[100:101], v[174:175], v[108:109], v[100:101] op_sel_hi:[0,1,1]
	v_pk_fma_f32 v[110:111], v[174:175], v[126:127], v[96:97] op_sel_hi:[0,1,1]
	v_mul_f32_e32 v96, v101, v101
	v_mul_f32_e32 v97, v103, v103
	v_fmac_f32_e32 v96, v100, v100
	v_fmac_f32_e32 v97, v102, v102
	v_lshlrev_b32_e32 v128, 16, v131
	v_and_b32_e32 v129, 0xffff0000, v131
	v_add_f32_e32 v96, v96, v97
	v_mul_f32_e32 v97, v111, v111
	v_pk_fma_f32 v[108:109], v[174:175], v[128:129], v[98:99] op_sel_hi:[0,1,1]
	v_fmac_f32_e32 v97, v110, v110
	v_add_f32_e32 v96, v97, v96
	v_mul_f32_e32 v97, v109, v109
	v_fmac_f32_e32 v97, v108, v108
	v_add_f32_e32 v96, v97, v96
	v_add_f32_e32 v99, v125, v96
	ds_bpermute_b32 v125, v176, v99
	v_lshl_add_u64 v[96:97], s[2:3], 0, v[172:173]
	v_lshl_add_u64 v[126:127], v[96:97], 0, v[156:157]
	global_store_dwordx4 v[126:127], v[104:107], off
	v_cvt_pk_bf16_f32 v98, v100, v101
	s_waitcnt lgkmcnt(0)
	v_add_f32_e32 v96, v99, v125
	ds_bpermute_b32 v97, v124, v96
	v_cvt_pk_bf16_f32 v99, v102, v103
	v_cvt_pk_bf16_f32 v100, v110, v111
	v_cvt_pk_bf16_f32 v101, v108, v109
	global_store_dwordx4 v[126:127], v[98:101], off offset:256
	s_and_saveexec_b64 s[12:13], vcc
	s_cbranch_execz .LBB0_836
	v_lshl_add_u64 v[98:99], v[170:171], 2, s[68:69]
	s_waitcnt lgkmcnt(0)
	v_add_f32_e32 v96, v96, v97
	v_mov_b32_e32 v237, v96
.LBB0_836:
	s_or_b64 exec, exec, s[12:13]
	v_add_u32_e32 v104, 48, v160
	v_ashrrev_i32_e32 v105, 31, v104
	v_lshlrev_b64 v[106:107], 12, v[104:105]
	s_waitcnt lgkmcnt(0)
	v_lshl_add_u64 v[96:97], s[40:41], 0, v[106:107]
	v_lshl_add_u64 v[96:97], v[96:97], 0, v[156:157]
	global_load_dwordx4 v[100:103], v[96:97], off
	s_nop 0
	global_load_dwordx4 v[96:99], v[96:97], off offset:256
	s_waitcnt vmcnt(5)
	v_lshlrev_b32_e32 v108, 16, v116
	v_and_b32_e32 v109, 0xffff0000, v116
	v_lshlrev_b32_e32 v110, 16, v117
	v_and_b32_e32 v111, 0xffff0000, v117
	v_lshlrev_b32_e32 v116, 16, v118
	v_and_b32_e32 v117, 0xffff0000, v118
	v_lshlrev_b32_e32 v118, 16, v119
	v_and_b32_e32 v119, 0xffff0000, v119
	v_pk_fma_f32 v[94:95], v[168:169], v[110:111], v[94:95] op_sel_hi:[0,1,1]
	v_pk_fma_f32 v[92:93], v[168:169], v[108:109], v[92:93] op_sel_hi:[0,1,1]
	v_pk_fma_f32 v[108:109], v[168:169], v[118:119], v[90:91] op_sel_hi:[0,1,1]
	v_pk_fma_f32 v[90:91], v[168:169], v[116:117], v[88:89] op_sel_hi:[0,1,1]
	v_mul_f32_e32 v88, v93, v93
	v_mul_f32_e32 v89, v95, v95
	v_fmac_f32_e32 v88, v92, v92
	v_fmac_f32_e32 v89, v94, v94
	v_add_f32_e32 v88, v88, v89
	v_mul_f32_e32 v89, v91, v91
	v_fmac_f32_e32 v89, v90, v90
	v_add_f32_e32 v88, v89, v88
	v_mul_f32_e32 v89, v109, v109
	v_fmac_f32_e32 v89, v108, v108
	v_add_f32_e32 v116, v89, v88
	v_cvt_pk_bf16_f32 v88, v92, v93
	v_cvt_pk_bf16_f32 v89, v94, v95
	s_waitcnt vmcnt(4)
	v_lshlrev_b32_e32 v92, 16, v112
	v_and_b32_e32 v93, 0xffff0000, v112
	v_lshlrev_b32_e32 v94, 16, v113
	v_and_b32_e32 v95, 0xffff0000, v113
	v_cvt_pk_bf16_f32 v90, v90, v91
	v_cvt_pk_bf16_f32 v91, v108, v109
	v_lshlrev_b32_e32 v108, 16, v114
	v_and_b32_e32 v109, 0xffff0000, v114
	v_pk_fma_f32 v[86:87], v[168:169], v[94:95], v[86:87] op_sel_hi:[0,1,1]
	v_pk_fma_f32 v[84:85], v[168:169], v[92:93], v[84:85] op_sel_hi:[0,1,1]
	v_pk_fma_f32 v[94:95], v[168:169], v[108:109], v[80:81] op_sel_hi:[0,1,1]
	v_mul_f32_e32 v80, v85, v85
	v_mul_f32_e32 v81, v87, v87
	v_fmac_f32_e32 v80, v84, v84
	v_fmac_f32_e32 v81, v86, v86
	v_lshlrev_b32_e32 v110, 16, v115
	v_and_b32_e32 v111, 0xffff0000, v115
	v_add_f32_e32 v80, v80, v81
	v_mul_f32_e32 v81, v95, v95
	v_pk_fma_f32 v[92:93], v[168:169], v[110:111], v[82:83] op_sel_hi:[0,1,1]
	v_fmac_f32_e32 v81, v94, v94
	v_add_f32_e32 v80, v81, v80
	v_mul_f32_e32 v81, v93, v93
	v_fmac_f32_e32 v81, v92, v92
	v_add_f32_e32 v80, v81, v80
	v_add_f32_e32 v83, v116, v80
	ds_bpermute_b32 v110, v176, v83
	v_lshl_add_u64 v[80:81], s[2:3], 0, v[122:123]
	v_lshl_add_u64 v[108:109], v[80:81], 0, v[156:157]
	global_store_dwordx4 v[108:109], v[88:91], off
	v_cvt_pk_bf16_f32 v82, v84, v85
	s_waitcnt lgkmcnt(0)
	v_add_f32_e32 v80, v83, v110
	ds_bpermute_b32 v81, v124, v80
	v_cvt_pk_bf16_f32 v83, v86, v87
	v_cvt_pk_bf16_f32 v84, v94, v95
	v_cvt_pk_bf16_f32 v85, v92, v93
	global_store_dwordx4 v[108:109], v[82:85], off offset:256
	s_and_saveexec_b64 s[12:13], vcc
	s_cbranch_execz .LBB0_838
	v_lshl_add_u64 v[82:83], v[120:121], 2, s[68:69]
	s_waitcnt lgkmcnt(0)
	v_add_f32_e32 v80, v80, v81
	v_mov_b32_e32 v238, v80
; __device__ __forceinline__ unsigned cvt_pk_bf16(float lo, float hi) { unsigned r; asm volatile("v_cvt_pk_bf16_f32 %0, %1, %2" : "=v"(r) : "v"(lo), "v"(hi)); return r; }
; #define UNPK4(q, lo, hi) const f32x4 lo = (f32x4){bf_lo((q).x), bf_hi((q).x), bf_lo((q).y), bf_hi((q).y)}, hi = (f32x4){bf_lo((q).z), bf_hi((q).z), bf_lo((q).w), bf_hi((q).w)}
;     __device__ __forceinline__ void operator()(EPI_ARGS) const {
;     ...
;         for (int g = 0; g < 8; ++g) {
;             const int ai = g >> 2, m = g & 3, row = ROW_OF(ai, m); float s = 0.f;
;             if (g < 7) {
; #pragma unroll
;                 for (int bj = 0; bj < 2; ++bj) xq[bj] = *(const u32x4*)(xn + (size_t)ROW_OF((g + 1) >> 2, (g + 1) & 3) * D + col0 + bj * 128);
;             }
; #pragma unroll
;             for (int bj = 0; bj < 2; ++bj) {
;                 const size_t off = (size_t)row * D + col0 + bj * 128;
;                 UNPK4(xc[bj], x0, x1);
;                 const f32x4 v0 = x0 * nr[g] + acc[ai][bj][m][0], v1 = x1 * nr[g] + acc[ai][bj][m][1];
;                 s += (v0[0] * v0[0] + v0[1] * v0[1]) + (v0[2] * v0[2] + v0[3] * v0[3]) + (v1[0] * v1[0] + v1[1] * v1[1]) + (v1[2] * v1[2] + v1[3] * v1[3]);
;                 u32x4 w; w.x = cvt_pk_bf16(v0[0], v0[1]); w.y = cvt_pk_bf16(v0[2], v0[3]); w.z = cvt_pk_bf16(v1[0], v1[1]); w.w = cvt_pk_bf16(v1[2], v1[3]); *(u32x4*)(xb + off) = w;
;             }
;             s += __shfl_xor(s, 16); s += __shfl_xor(s, 32);
;             if (fq == 0) __hip_atomic_fetch_add(ss + row, s, __ATOMIC_RELAXED, __HIP_MEMORY_SCOPE_AGENT);
;             if (g < 7) { xc[0] = xq[0]; xc[1] = xq[1]; }
;         }
.LBB0_838:
	s_or_b64 exec, exec, s[12:13]
	v_add_u32_e32 v88, 0x80, v160
	v_ashrrev_i32_e32 v89, 31, v88
	v_lshlrev_b64 v[90:91], 12, v[88:89]
	s_waitcnt lgkmcnt(0)
	v_lshl_add_u64 v[80:81], s[40:41], 0, v[90:91]
	v_lshl_add_u64 v[80:81], v[80:81], 0, v[156:157]
	global_load_dwordx4 v[84:87], v[80:81], off
	s_nop 0
	global_load_dwordx4 v[80:83], v[80:81], off offset:256
	s_waitcnt vmcnt(5)
	v_lshlrev_b32_e32 v92, 16, v100
	v_and_b32_e32 v93, 0xffff0000, v100
	v_lshlrev_b32_e32 v94, 16, v101
	v_and_b32_e32 v95, 0xffff0000, v101
	v_lshlrev_b32_e32 v100, 16, v102
	v_and_b32_e32 v101, 0xffff0000, v102
	v_lshlrev_b32_e32 v102, 16, v103
	v_and_b32_e32 v103, 0xffff0000, v103
	v_pk_fma_f32 v[78:79], v[166:167], v[94:95], v[78:79] op_sel_hi:[0,1,1]
	v_pk_fma_f32 v[76:77], v[166:167], v[92:93], v[76:77] op_sel_hi:[0,1,1]
	v_pk_fma_f32 v[92:93], v[166:167], v[102:103], v[74:75] op_sel_hi:[0,1,1]
	v_pk_fma_f32 v[74:75], v[166:167], v[100:101], v[72:73] op_sel_hi:[0,1,1]
	v_mul_f32_e32 v72, v77, v77
	v_mul_f32_e32 v73, v79, v79
	v_fmac_f32_e32 v72, v76, v76
	v_fmac_f32_e32 v73, v78, v78
	v_add_f32_e32 v72, v72, v73
	v_mul_f32_e32 v73, v75, v75
	v_fmac_f32_e32 v73, v74, v74
	v_add_f32_e32 v72, v73, v72
	v_mul_f32_e32 v73, v93, v93
	v_fmac_f32_e32 v73, v92, v92
	v_add_f32_e32 v100, v73, v72
	v_cvt_pk_bf16_f32 v72, v76, v77
	v_cvt_pk_bf16_f32 v73, v78, v79
	s_waitcnt vmcnt(4)
	v_lshlrev_b32_e32 v76, 16, v96
	v_and_b32_e32 v77, 0xffff0000, v96
	v_lshlrev_b32_e32 v78, 16, v97
	v_and_b32_e32 v79, 0xffff0000, v97
	v_cvt_pk_bf16_f32 v74, v74, v75
	v_cvt_pk_bf16_f32 v75, v92, v93
	v_lshlrev_b32_e32 v92, 16, v98
	v_and_b32_e32 v93, 0xffff0000, v98
	v_pk_fma_f32 v[70:71], v[166:167], v[78:79], v[70:71] op_sel_hi:[0,1,1]
	v_pk_fma_f32 v[68:69], v[166:167], v[76:77], v[68:69] op_sel_hi:[0,1,1]
	v_pk_fma_f32 v[78:79], v[166:167], v[92:93], v[64:65] op_sel_hi:[0,1,1]
	v_mul_f32_e32 v64, v69, v69
	v_mul_f32_e32 v65, v71, v71
	v_fmac_f32_e32 v64, v68, v68
	v_fmac_f32_e32 v65, v70, v70
	v_lshlrev_b32_e32 v94, 16, v99
	v_and_b32_e32 v95, 0xffff0000, v99
	v_add_f32_e32 v64, v64, v65
	v_mul_f32_e32 v65, v79, v79
	v_pk_fma_f32 v[76:77], v[166:167], v[94:95], v[66:67] op_sel_hi:[0,1,1]
	v_fmac_f32_e32 v65, v78, v78
	v_add_f32_e32 v64, v65, v64
	v_mul_f32_e32 v65, v77, v77
	v_fmac_f32_e32 v65, v76, v76
	v_add_f32_e32 v64, v65, v64
	v_add_f32_e32 v67, v100, v64
	ds_bpermute_b32 v94, v176, v67
	v_lshl_add_u64 v[64:65], s[2:3], 0, v[106:107]
	v_lshl_add_u64 v[92:93], v[64:65], 0, v[156:157]
	global_store_dwordx4 v[92:93], v[72:75], off
	v_cvt_pk_bf16_f32 v66, v68, v69
	s_waitcnt lgkmcnt(0)
	v_add_f32_e32 v64, v67, v94
	ds_bpermute_b32 v65, v124, v64
	v_cvt_pk_bf16_f32 v67, v70, v71
	v_cvt_pk_bf16_f32 v68, v78, v79
	v_cvt_pk_bf16_f32 v69, v76, v77
	global_store_dwordx4 v[92:93], v[66:69], off offset:256
	s_and_saveexec_b64 s[12:13], vcc
	s_cbranch_execz .LBB0_840
	v_lshl_add_u64 v[66:67], v[104:105], 2, s[68:69]
	s_waitcnt lgkmcnt(0)
	v_add_f32_e32 v64, v64, v65
	v_mov_b32_e32 v239, v64
.LBB0_840:
	s_or_b64 exec, exec, s[12:13]
	v_add_u32_e32 v72, 0x90, v160
	v_ashrrev_i32_e32 v73, 31, v72
	v_lshlrev_b64 v[74:75], 12, v[72:73]
	s_waitcnt lgkmcnt(0)
	v_lshl_add_u64 v[64:65], s[40:41], 0, v[74:75]
	v_lshl_add_u64 v[64:65], v[64:65], 0, v[156:157]
	global_load_dwordx4 v[68:71], v[64:65], off
	s_nop 0
	global_load_dwordx4 v[64:67], v[64:65], off offset:256
	s_waitcnt vmcnt(5)
	v_lshlrev_b32_e32 v76, 16, v84
	v_and_b32_e32 v77, 0xffff0000, v84
	v_lshlrev_b32_e32 v78, 16, v85
	v_and_b32_e32 v79, 0xffff0000, v85
	v_lshlrev_b32_e32 v84, 16, v86
	v_and_b32_e32 v85, 0xffff0000, v86
	v_lshlrev_b32_e32 v86, 16, v87
	v_and_b32_e32 v87, 0xffff0000, v87
	v_pk_fma_f32 v[62:63], v[164:165], v[78:79], v[62:63] op_sel_hi:[0,1,1]
	v_pk_fma_f32 v[60:61], v[164:165], v[76:77], v[60:61] op_sel_hi:[0,1,1]
	v_pk_fma_f32 v[76:77], v[164:165], v[86:87], v[58:59] op_sel_hi:[0,1,1]
	v_pk_fma_f32 v[58:59], v[164:165], v[84:85], v[56:57] op_sel_hi:[0,1,1]
	v_mul_f32_e32 v56, v61, v61
	v_mul_f32_e32 v57, v63, v63
	v_fmac_f32_e32 v56, v60, v60
	v_fmac_f32_e32 v57, v62, v62
	v_add_f32_e32 v56, v56, v57
	v_mul_f32_e32 v57, v59, v59
	v_fmac_f32_e32 v57, v58, v58
	v_add_f32_e32 v56, v57, v56
	v_mul_f32_e32 v57, v77, v77
	v_fmac_f32_e32 v57, v76, v76
	v_add_f32_e32 v84, v57, v56
	v_cvt_pk_bf16_f32 v56, v60, v61
	v_cvt_pk_bf16_f32 v57, v62, v63
	s_waitcnt vmcnt(4)
	v_lshlrev_b32_e32 v60, 16, v80
	v_and_b32_e32 v61, 0xffff0000, v80
	v_lshlrev_b32_e32 v62, 16, v81
	v_and_b32_e32 v63, 0xffff0000, v81
	v_cvt_pk_bf16_f32 v58, v58, v59
	v_cvt_pk_bf16_f32 v59, v76, v77
	v_lshlrev_b32_e32 v76, 16, v82
	v_and_b32_e32 v77, 0xffff0000, v82
	v_pk_fma_f32 v[54:55], v[164:165], v[62:63], v[54:55] op_sel_hi:[0,1,1]
	v_pk_fma_f32 v[52:53], v[164:165], v[60:61], v[52:53] op_sel_hi:[0,1,1]
	v_pk_fma_f32 v[62:63], v[164:165], v[76:77], v[48:49] op_sel_hi:[0,1,1]
	v_mul_f32_e32 v48, v53, v53
	v_mul_f32_e32 v49, v55, v55
	v_fmac_f32_e32 v48, v52, v52
	v_fmac_f32_e32 v49, v54, v54
	v_lshlrev_b32_e32 v78, 16, v83
	v_and_b32_e32 v79, 0xffff0000, v83
	v_add_f32_e32 v48, v48, v49
	v_mul_f32_e32 v49, v63, v63
	v_pk_fma_f32 v[60:61], v[164:165], v[78:79], v[50:51] op_sel_hi:[0,1,1]
	v_fmac_f32_e32 v49, v62, v62
	v_add_f32_e32 v48, v49, v48
	v_mul_f32_e32 v49, v61, v61
	v_fmac_f32_e32 v49, v60, v60
	v_add_f32_e32 v48, v49, v48
	v_add_f32_e32 v51, v84, v48
	ds_bpermute_b32 v78, v176, v51
	v_lshl_add_u64 v[48:49], s[2:3], 0, v[90:91]
	v_lshl_add_u64 v[76:77], v[48:49], 0, v[156:157]
	global_store_dwordx4 v[76:77], v[56:59], off
	v_cvt_pk_bf16_f32 v50, v52, v53
	s_waitcnt lgkmcnt(0)
	v_add_f32_e32 v48, v51, v78
	ds_bpermute_b32 v49, v124, v48
	v_cvt_pk_bf16_f32 v51, v54, v55
	v_cvt_pk_bf16_f32 v52, v62, v63
	v_cvt_pk_bf16_f32 v53, v60, v61
	global_store_dwordx4 v[76:77], v[50:53], off offset:256
	s_and_saveexec_b64 s[12:13], vcc
	s_cbranch_execz .LBB0_842
	v_lshl_add_u64 v[50:51], v[88:89], 2, s[68:69]
	s_waitcnt lgkmcnt(0)
	v_add_f32_e32 v48, v48, v49
	v_mov_b32_e32 v240, v48
; __device__ __forceinline__ unsigned cvt_pk_bf16(float lo, float hi) { unsigned r; asm volatile("v_cvt_pk_bf16_f32 %0, %1, %2" : "=v"(r) : "v"(lo), "v"(hi)); return r; }
; #define UNPK4(q, lo, hi) const f32x4 lo = (f32x4){bf_lo((q).x), bf_hi((q).x), bf_lo((q).y), bf_hi((q).y)}, hi = (f32x4){bf_lo((q).z), bf_hi((q).z), bf_lo((q).w), bf_hi((q).w)}
;     __device__ __forceinline__ void operator()(EPI_ARGS) const {
;     ...
;         for (int g = 0; g < 8; ++g) {
;             const int ai = g >> 2, m = g & 3, row = ROW_OF(ai, m); float s = 0.f;
;             if (g < 7) {
; #pragma unroll
;                 for (int bj = 0; bj < 2; ++bj) xq[bj] = *(const u32x4*)(xn + (size_t)ROW_OF((g + 1) >> 2, (g + 1) & 3) * D + col0 + bj * 128);
;             }
; #pragma unroll
;             for (int bj = 0; bj < 2; ++bj) {
;                 const size_t off = (size_t)row * D + col0 + bj * 128;
;                 UNPK4(xc[bj], x0, x1);
;                 const f32x4 v0 = x0 * nr[g] + acc[ai][bj][m][0], v1 = x1 * nr[g] + acc[ai][bj][m][1];
;                 s += (v0[0] * v0[0] + v0[1] * v0[1]) + (v0[2] * v0[2] + v0[3] * v0[3]) + (v1[0] * v1[0] + v1[1] * v1[1]) + (v1[2] * v1[2] + v1[3] * v1[3]);
;                 u32x4 w; w.x = cvt_pk_bf16(v0[0], v0[1]); w.y = cvt_pk_bf16(v0[2], v0[3]); w.z = cvt_pk_bf16(v1[0], v1[1]); w.w = cvt_pk_bf16(v1[2], v1[3]); *(u32x4*)(xb + off) = w;
;             }
;             s += __shfl_xor(s, 16); s += __shfl_xor(s, 32);
;             if (fq == 0) __hip_atomic_fetch_add(ss + row, s, __ATOMIC_RELAXED, __HIP_MEMORY_SCOPE_AGENT);
;             if (g < 7) { xc[0] = xq[0]; xc[1] = xq[1]; }
;         }
.LBB0_842:
	s_or_b64 exec, exec, s[12:13]
	v_add_u32_e32 v56, 0xa0, v160
	v_ashrrev_i32_e32 v57, 31, v56
	v_lshlrev_b64 v[58:59], 12, v[56:57]
	s_waitcnt lgkmcnt(0)
	v_lshl_add_u64 v[48:49], s[40:41], 0, v[58:59]
	v_lshl_add_u64 v[48:49], v[48:49], 0, v[156:157]
	global_load_dwordx4 v[52:55], v[48:49], off
	s_nop 0
	global_load_dwordx4 v[48:51], v[48:49], off offset:256
	s_waitcnt vmcnt(5)
	v_lshlrev_b32_e32 v60, 16, v68
	v_and_b32_e32 v61, 0xffff0000, v68
	v_lshlrev_b32_e32 v62, 16, v69
	v_and_b32_e32 v63, 0xffff0000, v69
	v_lshlrev_b32_e32 v68, 16, v70
	v_and_b32_e32 v69, 0xffff0000, v70
	v_lshlrev_b32_e32 v70, 16, v71
	v_and_b32_e32 v71, 0xffff0000, v71
	v_pk_fma_f32 v[46:47], v[162:163], v[62:63], v[46:47] op_sel_hi:[0,1,1]
	v_pk_fma_f32 v[44:45], v[162:163], v[60:61], v[44:45] op_sel_hi:[0,1,1]
	v_pk_fma_f32 v[60:61], v[162:163], v[70:71], v[42:43] op_sel_hi:[0,1,1]
	v_pk_fma_f32 v[42:43], v[162:163], v[68:69], v[40:41] op_sel_hi:[0,1,1]
	v_mul_f32_e32 v40, v45, v45
	v_mul_f32_e32 v41, v47, v47
	v_fmac_f32_e32 v40, v44, v44
	v_fmac_f32_e32 v41, v46, v46
	v_add_f32_e32 v40, v40, v41
	v_mul_f32_e32 v41, v43, v43
	v_fmac_f32_e32 v41, v42, v42
	v_add_f32_e32 v40, v41, v40
	v_mul_f32_e32 v41, v61, v61
	v_fmac_f32_e32 v41, v60, v60
	v_add_f32_e32 v68, v41, v40
	v_cvt_pk_bf16_f32 v40, v44, v45
	v_cvt_pk_bf16_f32 v41, v46, v47
	s_waitcnt vmcnt(4)
	v_lshlrev_b32_e32 v44, 16, v64
	v_and_b32_e32 v45, 0xffff0000, v64
	v_lshlrev_b32_e32 v46, 16, v65
	v_and_b32_e32 v47, 0xffff0000, v65
	v_cvt_pk_bf16_f32 v42, v42, v43
	v_cvt_pk_bf16_f32 v43, v60, v61
	v_lshlrev_b32_e32 v60, 16, v66
	v_and_b32_e32 v61, 0xffff0000, v66
	v_pk_fma_f32 v[38:39], v[162:163], v[46:47], v[38:39] op_sel_hi:[0,1,1]
	v_pk_fma_f32 v[36:37], v[162:163], v[44:45], v[36:37] op_sel_hi:[0,1,1]
	v_pk_fma_f32 v[46:47], v[162:163], v[60:61], v[32:33] op_sel_hi:[0,1,1]
	v_mul_f32_e32 v32, v37, v37
	v_mul_f32_e32 v33, v39, v39
	v_fmac_f32_e32 v32, v36, v36
	v_fmac_f32_e32 v33, v38, v38
	v_lshlrev_b32_e32 v62, 16, v67
	v_and_b32_e32 v63, 0xffff0000, v67
	v_add_f32_e32 v32, v32, v33
	v_mul_f32_e32 v33, v47, v47
	v_pk_fma_f32 v[44:45], v[162:163], v[62:63], v[34:35] op_sel_hi:[0,1,1]
	v_fmac_f32_e32 v33, v46, v46
	v_add_f32_e32 v32, v33, v32
	v_mul_f32_e32 v33, v45, v45
	v_fmac_f32_e32 v33, v44, v44
	v_add_f32_e32 v32, v33, v32
	v_add_f32_e32 v35, v68, v32
	ds_bpermute_b32 v62, v176, v35
	v_lshl_add_u64 v[32:33], s[2:3], 0, v[74:75]
	v_lshl_add_u64 v[60:61], v[32:33], 0, v[156:157]
	global_store_dwordx4 v[60:61], v[40:43], off
	v_cvt_pk_bf16_f32 v34, v36, v37
	s_waitcnt lgkmcnt(0)
	v_add_f32_e32 v32, v35, v62
	ds_bpermute_b32 v33, v124, v32
	v_cvt_pk_bf16_f32 v35, v38, v39
	v_cvt_pk_bf16_f32 v36, v46, v47
	v_cvt_pk_bf16_f32 v37, v44, v45
	global_store_dwordx4 v[60:61], v[34:37], off offset:256
	s_and_saveexec_b64 s[12:13], vcc
	s_cbranch_execz .LBB0_844
	v_lshl_add_u64 v[34:35], v[72:73], 2, s[68:69]
	s_waitcnt lgkmcnt(0)
	v_add_f32_e32 v32, v32, v33
	v_mov_b32_e32 v241, v32
; __device__ __forceinline__ unsigned cvt_pk_bf16(float lo, float hi) { unsigned r; asm volatile("v_cvt_pk_bf16_f32 %0, %1, %2" : "=v"(r) : "v"(lo), "v"(hi)); return r; }
; #define UNPK4(q, lo, hi) const f32x4 lo = (f32x4){bf_lo((q).x), bf_hi((q).x), bf_lo((q).y), bf_hi((q).y)}, hi = (f32x4){bf_lo((q).z), bf_hi((q).z), bf_lo((q).w), bf_hi((q).w)}
;     __device__ __forceinline__ void operator()(EPI_ARGS) const {
;     ...
;         for (int g = 0; g < 8; ++g) {
;             const int ai = g >> 2, m = g & 3, row = ROW_OF(ai, m); float s = 0.f;
;             if (g < 7) {
; #pragma unroll
;                 for (int bj = 0; bj < 2; ++bj) xq[bj] = *(const u32x4*)(xn + (size_t)ROW_OF((g + 1) >> 2, (g + 1) & 3) * D + col0 + bj * 128);
;             }
; #pragma unroll
;             for (int bj = 0; bj < 2; ++bj) {
;                 const size_t off = (size_t)row * D + col0 + bj * 128;
;                 UNPK4(xc[bj], x0, x1);
;                 const f32x4 v0 = x0 * nr[g] + acc[ai][bj][m][0], v1 = x1 * nr[g] + acc[ai][bj][m][1];
;                 s += (v0[0] * v0[0] + v0[1] * v0[1]) + (v0[2] * v0[2] + v0[3] * v0[3]) + (v1[0] * v1[0] + v1[1] * v1[1]) + (v1[2] * v1[2] + v1[3] * v1[3]);
;                 u32x4 w; w.x = cvt_pk_bf16(v0[0], v0[1]); w.y = cvt_pk_bf16(v0[2], v0[3]); w.z = cvt_pk_bf16(v1[0], v1[1]); w.w = cvt_pk_bf16(v1[2], v1[3]); *(u32x4*)(xb + off) = w;
;             }
;             s += __shfl_xor(s, 16); s += __shfl_xor(s, 32);
;             if (fq == 0) __hip_atomic_fetch_add(ss + row, s, __ATOMIC_RELAXED, __HIP_MEMORY_SCOPE_AGENT);
;             if (g < 7) { xc[0] = xq[0]; xc[1] = xq[1]; }
;         }
.LBB0_844:
	s_or_b64 exec, exec, s[12:13]
	v_add_u32_e32 v40, 0xb0, v160
	v_ashrrev_i32_e32 v41, 31, v40
	v_lshlrev_b64 v[42:43], 12, v[40:41]
	s_waitcnt lgkmcnt(0)
	v_lshl_add_u64 v[32:33], s[40:41], 0, v[42:43]
	v_lshl_add_u64 v[32:33], v[32:33], 0, v[156:157]
	global_load_dwordx4 v[36:39], v[32:33], off
	s_nop 0
	global_load_dwordx4 v[32:35], v[32:33], off offset:256
	s_waitcnt vmcnt(5)
	v_lshlrev_b32_e32 v44, 16, v52
	v_and_b32_e32 v45, 0xffff0000, v52
	v_lshlrev_b32_e32 v46, 16, v53
	v_and_b32_e32 v47, 0xffff0000, v53
	v_lshlrev_b32_e32 v52, 16, v54
	v_and_b32_e32 v53, 0xffff0000, v54
	v_lshlrev_b32_e32 v54, 16, v55
	v_and_b32_e32 v55, 0xffff0000, v55
	v_pk_fma_f32 v[30:31], v[158:159], v[46:47], v[30:31] op_sel_hi:[0,1,1]
	v_pk_fma_f32 v[28:29], v[158:159], v[44:45], v[28:29] op_sel_hi:[0,1,1]
	v_pk_fma_f32 v[44:45], v[158:159], v[54:55], v[26:27] op_sel_hi:[0,1,1]
	v_pk_fma_f32 v[26:27], v[158:159], v[52:53], v[24:25] op_sel_hi:[0,1,1]
	v_mul_f32_e32 v24, v29, v29
	v_mul_f32_e32 v25, v31, v31
	v_fmac_f32_e32 v24, v28, v28
	v_fmac_f32_e32 v25, v30, v30
	v_add_f32_e32 v24, v24, v25
	v_mul_f32_e32 v25, v27, v27
	v_fmac_f32_e32 v25, v26, v26
	v_add_f32_e32 v24, v25, v24
	v_mul_f32_e32 v25, v45, v45
	v_fmac_f32_e32 v25, v44, v44
	v_add_f32_e32 v52, v25, v24
	v_cvt_pk_bf16_f32 v24, v28, v29
	v_cvt_pk_bf16_f32 v25, v30, v31
	s_waitcnt vmcnt(4)
	v_lshlrev_b32_e32 v28, 16, v48
	v_and_b32_e32 v29, 0xffff0000, v48
	v_lshlrev_b32_e32 v30, 16, v49
	v_and_b32_e32 v31, 0xffff0000, v49
	v_cvt_pk_bf16_f32 v26, v26, v27
	v_cvt_pk_bf16_f32 v27, v44, v45
	v_lshlrev_b32_e32 v44, 16, v50
	v_and_b32_e32 v45, 0xffff0000, v50
	v_pk_fma_f32 v[22:23], v[158:159], v[30:31], v[22:23] op_sel_hi:[0,1,1]
	v_pk_fma_f32 v[20:21], v[158:159], v[28:29], v[20:21] op_sel_hi:[0,1,1]
	v_pk_fma_f32 v[30:31], v[158:159], v[44:45], v[16:17] op_sel_hi:[0,1,1]
	v_mul_f32_e32 v16, v21, v21
	v_mul_f32_e32 v17, v23, v23
	v_fmac_f32_e32 v16, v20, v20
	v_fmac_f32_e32 v17, v22, v22
	v_lshlrev_b32_e32 v46, 16, v51
	v_and_b32_e32 v47, 0xffff0000, v51
	v_add_f32_e32 v16, v16, v17
	v_mul_f32_e32 v17, v31, v31
	v_pk_fma_f32 v[28:29], v[158:159], v[46:47], v[18:19] op_sel_hi:[0,1,1]
	v_fmac_f32_e32 v17, v30, v30
	v_add_f32_e32 v16, v17, v16
	v_mul_f32_e32 v17, v29, v29
	v_fmac_f32_e32 v17, v28, v28
	v_add_f32_e32 v16, v17, v16
	v_add_f32_e32 v19, v52, v16
	ds_bpermute_b32 v46, v176, v19
	v_lshl_add_u64 v[16:17], s[2:3], 0, v[58:59]
	v_lshl_add_u64 v[44:45], v[16:17], 0, v[156:157]
	global_store_dwordx4 v[44:45], v[24:27], off
	v_cvt_pk_bf16_f32 v18, v20, v21
	s_waitcnt lgkmcnt(0)
	v_add_f32_e32 v16, v19, v46
	ds_bpermute_b32 v17, v124, v16
	v_cvt_pk_bf16_f32 v19, v22, v23
	v_cvt_pk_bf16_f32 v20, v30, v31
	v_cvt_pk_bf16_f32 v21, v28, v29
	global_store_dwordx4 v[44:45], v[18:21], off offset:256
	s_and_saveexec_b64 s[12:13], vcc
	s_cbranch_execz .LBB0_846
	v_lshl_add_u64 v[18:19], v[56:57], 2, s[68:69]
	s_waitcnt lgkmcnt(0)
	v_add_f32_e32 v16, v16, v17
	v_mov_b32_e32 v242, v16
.LBB0_846:
	s_or_b64 exec, exec, s[12:13]
	s_waitcnt vmcnt(3)
	v_lshlrev_b32_e32 v16, 16, v36
	s_waitcnt lgkmcnt(0)
	v_and_b32_e32 v17, 0xffff0000, v36
	v_lshlrev_b32_e32 v18, 16, v37
	v_and_b32_e32 v19, 0xffff0000, v37
	v_lshlrev_b32_e32 v20, 16, v38
	v_and_b32_e32 v21, 0xffff0000, v38
	v_lshlrev_b32_e32 v22, 16, v39
	v_and_b32_e32 v23, 0xffff0000, v39
	v_pk_fma_f32 v[14:15], v[154:155], v[18:19], v[14:15] op_sel_hi:[0,1,1]
	v_pk_fma_f32 v[12:13], v[154:155], v[16:17], v[12:13] op_sel_hi:[0,1,1]
	v_pk_fma_f32 v[16:17], v[154:155], v[22:23], v[10:11] op_sel_hi:[0,1,1]
	v_pk_fma_f32 v[10:11], v[154:155], v[20:21], v[8:9] op_sel_hi:[0,1,1]
	v_mul_f32_e32 v8, v13, v13
	v_mul_f32_e32 v9, v15, v15
	v_fmac_f32_e32 v8, v12, v12
	v_fmac_f32_e32 v9, v14, v14
	v_add_f32_e32 v8, v8, v9
	v_mul_f32_e32 v9, v11, v11
	v_fmac_f32_e32 v9, v10, v10
	v_add_f32_e32 v8, v9, v8
	v_mul_f32_e32 v9, v17, v17
	v_fmac_f32_e32 v9, v16, v16
	v_add_f32_e32 v20, v9, v8
	v_cvt_pk_bf16_f32 v8, v12, v13
	v_cvt_pk_bf16_f32 v9, v14, v15
	s_waitcnt vmcnt(2)
	v_lshlrev_b32_e32 v12, 16, v32
	v_and_b32_e32 v13, 0xffff0000, v32
	v_lshlrev_b32_e32 v14, 16, v33
	v_and_b32_e32 v15, 0xffff0000, v33
	v_cvt_pk_bf16_f32 v10, v10, v11
	v_cvt_pk_bf16_f32 v11, v16, v17
	v_lshlrev_b32_e32 v16, 16, v34
	v_and_b32_e32 v17, 0xffff0000, v34
	v_pk_fma_f32 v[6:7], v[154:155], v[14:15], v[6:7] op_sel_hi:[0,1,1]
	v_pk_fma_f32 v[4:5], v[154:155], v[12:13], v[4:5] op_sel_hi:[0,1,1]
	v_pk_fma_f32 v[14:15], v[154:155], v[16:17], v[0:1] op_sel_hi:[0,1,1]
	v_mul_f32_e32 v0, v5, v5
	v_mul_f32_e32 v1, v7, v7
	v_fmac_f32_e32 v0, v4, v4
	v_fmac_f32_e32 v1, v6, v6
	v_lshlrev_b32_e32 v18, 16, v35
	v_and_b32_e32 v19, 0xffff0000, v35
	v_add_f32_e32 v0, v0, v1
	v_mul_f32_e32 v1, v15, v15
	v_pk_fma_f32 v[12:13], v[154:155], v[18:19], v[2:3] op_sel_hi:[0,1,1]
	v_fmac_f32_e32 v1, v14, v14
	v_add_f32_e32 v0, v1, v0
	v_mul_f32_e32 v1, v13, v13
	v_fmac_f32_e32 v1, v12, v12
	v_add_f32_e32 v0, v1, v0
	v_add_f32_e32 v3, v20, v0
	ds_bpermute_b32 v18, v176, v3
	v_lshl_add_u64 v[0:1], s[2:3], 0, v[42:43]
	v_lshl_add_u64 v[16:17], v[152:153], 1, v[0:1]
	global_store_dwordx4 v[16:17], v[8:11], off
	v_cvt_pk_bf16_f32 v2, v4, v5
	s_waitcnt lgkmcnt(0)
	v_add_f32_e32 v0, v3, v18
	ds_bpermute_b32 v1, v124, v0
	v_cvt_pk_bf16_f32 v3, v6, v7
	v_cvt_pk_bf16_f32 v4, v14, v15
	v_cvt_pk_bf16_f32 v5, v12, v13
	global_store_dwordx4 v[16:17], v[2:5], off offset:256
	s_and_saveexec_b64 s[12:13], vcc
	s_cbranch_execz .LBB0_848
	v_lshl_add_u64 v[2:3], v[40:41], 2, s[68:69]
	s_waitcnt lgkmcnt(0)
	v_add_f32_e32 v0, v0, v1
	global_atomic_add_f32 v[2:3], v0, off
	global_atomic_add_f32 v[2:3], v236, off offset:-704
	global_atomic_add_f32 v[2:3], v237, off offset:-640
	global_atomic_add_f32 v[2:3], v238, off offset:-576
	global_atomic_add_f32 v[2:3], v239, off offset:-512
	global_atomic_add_f32 v[2:3], v240, off offset:-192
	global_atomic_add_f32 v[2:3], v241, off offset:-128
	global_atomic_add_f32 v[2:3], v242, off offset:-64

; #define UNPK4(q, lo, hi) const f32x4 lo = (f32x4){bf_lo((q).x), bf_hi((q).x), bf_lo((q).y), bf_hi((q).y)}, hi = (f32x4){bf_lo((q).z), bf_hi((q).z), bf_lo((q).w), bf_hi((q).w)}
;     __device__ __forceinline__ void operator()(f32x4 (&acc)[2][2][4][2], const Unit& u, int wr, int wc, int fr, int fq) const {
;         const int col0 = u.pn * 256 + wc * 32 + 8 * fq;
;         u32x4 xc[2], xn[2];
; #pragma unroll
;         for (int bj = 0; bj < 2; ++bj) xc[bj] = *(const u32x4*)(xb + (size_t)ROW_OF(0, 0) * D + col0 + bj * 128);
; #pragma unroll
;         for (int g = 0; g < 8; ++g) {
;             const int ai = g >> 2, m = g & 3, row = ROW_OF(ai, m); float s = 0.f;
;             if (g < 7) {
; #pragma unroll
;                 for (int bj = 0; bj < 2; ++bj) xn[bj] = *(const u32x4*)(xb + (size_t)ROW_OF((g + 1) >> 2, (g + 1) & 3) * D + col0 + bj * 128);
;             }
; #pragma unroll
;             for (int bj = 0; bj < 2; ++bj) {
;                 UNPK4(xc[bj], x0, x1);
;                 const f32x4 v0 = x0 + acc[ai][bj][m][0], v1 = x1 + acc[ai][bj][m][1];
;                 acc[ai][bj][m][0] = v0; acc[ai][bj][m][1] = v1;
;                 s += (v0[0] * v0[0] + v0[1] * v0[1]) + (v0[2] * v0[2] + v0[3] * v0[3]) + (v1[0] * v1[0] + v1[1] * v1[1]) + (v1[2] * v1[2] + v1[3] * v1[3]);
;             }
;             s += __shfl_xor(s, 16); s += __shfl_xor(s, 32);
;             if (fq == 0) __hip_atomic_fetch_add(ss + row, s, __ATOMIC_RELAXED, __HIP_MEMORY_SCOPE_AGENT);
;             if (g < 7) { xc[0] = xn[0]; xc[1] = xn[1]; }
;         }
.LBB0_1080:
	s_lshl_b32 s1, s0, 8
	v_mov_b32_e32 v170, v189
	v_mov_b32_e32 v128, v188
	s_add_i32 s1, s1, s43
	s_nop 0
	v_add_u32_e32 v162, s1, v128
	v_lshl_add_u32 v168, v170, 3, s48
	v_ashrrev_i32_e32 v163, 31, v162
	v_lshlrev_b64 v[128:129], 12, v[162:163]
	v_ashrrev_i32_e32 v169, 31, v168
	v_lshl_add_u64 v[128:129], s[74:75], 0, v[128:129]
	v_lshlrev_b64 v[130:131], 1, v[168:169]
	v_lshl_add_u64 v[128:129], v[128:129], 0, v[130:131]
	global_load_dwordx4 v[148:151], v[128:129], off
	global_load_dwordx4 v[154:157], v[128:129], off offset:256
	v_add_u32_e32 v152, 16, v162
	v_ashrrev_i32_e32 v153, 31, v152
	v_lshlrev_b64 v[128:129], 12, v[152:153]
	v_lshl_add_u64 v[128:129], s[74:75], 0, v[128:129]
	v_lshl_add_u64 v[128:129], v[128:129], 0, v[130:131]
	global_load_dwordx4 v[132:135], v[128:129], off
	s_nop 0
	global_load_dwordx4 v[128:131], v[128:129], off offset:256
	v_cmp_eq_u32_e32 vcc, 0, v170
	v_lshl_add_u64 v[174:175], v[162:163], 2, s[14:15]
	s_waitcnt vmcnt(0)
	v_lshlrev_b32_e32 v158, 16, v148
	v_and_b32_e32 v159, 0xffff0000, v148
	v_lshlrev_b32_e32 v148, 16, v149
	v_and_b32_e32 v149, 0xffff0000, v149
	v_lshlrev_b32_e32 v160, 16, v150
	v_and_b32_e32 v161, 0xffff0000, v150
	v_lshlrev_b32_e32 v150, 16, v151
	v_and_b32_e32 v151, 0xffff0000, v151
	v_lshlrev_b32_e32 v164, 16, v154
	v_and_b32_e32 v165, 0xffff0000, v154
	v_lshlrev_b32_e32 v154, 16, v155
	v_and_b32_e32 v155, 0xffff0000, v155
	v_lshlrev_b32_e32 v166, 16, v156
	v_and_b32_e32 v167, 0xffff0000, v156
	v_pk_add_f32 v[126:127], v[126:127], v[148:149]
	v_pk_add_f32 v[148:149], v[124:125], v[158:159]
	v_pk_add_f32 v[122:123], v[122:123], v[150:151]
	v_pk_add_f32 v[150:151], v[118:119], v[154:155]
	v_pk_add_f32 v[154:155], v[116:117], v[164:165]
	v_lshlrev_b32_e32 v156, 16, v157
	v_and_b32_e32 v157, 0xffff0000, v157
	v_pk_add_f32 v[124:125], v[120:121], v[160:161]
	v_pk_add_f32 v[158:159], v[112:113], v[166:167]
	v_mul_f32_e32 v112, v149, v149
	v_mul_f32_e32 v113, v127, v127
	v_mul_f32_e32 v116, v155, v155
	v_mul_f32_e32 v117, v151, v151
	v_pk_add_f32 v[156:157], v[114:115], v[156:157]
	v_mul_f32_e32 v114, v125, v125
	v_mul_f32_e32 v118, v159, v159
	v_fmac_f32_e32 v112, v148, v148
	v_fmac_f32_e32 v113, v126, v126
	v_fmac_f32_e32 v116, v154, v154
	v_fmac_f32_e32 v117, v150, v150
	v_mul_f32_e32 v115, v123, v123
	v_mul_f32_e32 v119, v157, v157
	v_fmac_f32_e32 v114, v124, v124
	v_fmac_f32_e32 v118, v158, v158
	v_add_f32_e32 v112, v112, v113
	v_add_f32_e32 v113, v116, v117
	v_fmac_f32_e32 v115, v122, v122
	v_fmac_f32_e32 v119, v156, v156
	v_add_f32_e32 v112, v114, v112
	v_add_f32_e32 v113, v118, v113
	v_add_f32_e32 v112, v115, v112
	v_add_f32_e32 v113, v119, v113
	v_add_f32_e32 v112, v112, v113
	ds_bpermute_b32 v113, v191, v112
	s_waitcnt lgkmcnt(0)
	v_add_f32_e32 v112, v112, v113
	ds_bpermute_b32 v113, v192, v112
	s_and_saveexec_b64 s[4:5], vcc
	s_cbranch_execz .LBB0_1082
	s_waitcnt lgkmcnt(0)
	v_add_f32_e32 v112, v112, v113
	v_mov_b32_e32 v236, v112
.LBB0_1082:
	s_or_b64 exec, exec, s[4:5]
	v_add_u32_e32 v120, 32, v162
	v_ashrrev_i32_e32 v121, 31, v120
	s_waitcnt lgkmcnt(0)
	v_lshlrev_b64 v[112:113], 12, v[120:121]
	v_lshl_add_u64 v[112:113], s[74:75], 0, v[112:113]
	v_lshl_add_u64 v[112:113], v[168:169], 1, v[112:113]
	global_load_dwordx4 v[116:119], v[112:113], off
	s_nop 0
	global_load_dwordx4 v[112:115], v[112:113], off offset:256
	v_lshlrev_b32_e32 v160, 16, v132
	v_and_b32_e32 v161, 0xffff0000, v132
	v_lshlrev_b32_e32 v132, 16, v133
	v_and_b32_e32 v133, 0xffff0000, v133
	v_lshlrev_b32_e32 v164, 16, v134
	v_and_b32_e32 v165, 0xffff0000, v134
	v_lshlrev_b32_e32 v134, 16, v135
	v_and_b32_e32 v135, 0xffff0000, v135
	v_pk_add_f32 v[132:133], v[110:111], v[132:133]
	v_pk_add_f32 v[160:161], v[108:109], v[160:161]
	v_pk_add_f32 v[110:111], v[106:107], v[134:135]
	v_pk_add_f32 v[134:135], v[104:105], v[164:165]
	v_mul_f32_e32 v104, v161, v161
	v_mul_f32_e32 v105, v133, v133
	v_fmac_f32_e32 v104, v160, v160
	v_fmac_f32_e32 v105, v132, v132
	v_add_f32_e32 v104, v104, v105
	v_mul_f32_e32 v105, v135, v135
	v_fmac_f32_e32 v105, v134, v134
	v_add_f32_e32 v104, v105, v104
	v_mul_f32_e32 v105, v111, v111
	v_fmac_f32_e32 v105, v110, v110
	v_add_f32_e32 v166, v105, v104
	v_lshlrev_b32_e32 v104, 16, v128
	v_and_b32_e32 v105, 0xffff0000, v128
	v_lshlrev_b32_e32 v106, 16, v129
	v_and_b32_e32 v107, 0xffff0000, v129
	v_lshlrev_b32_e32 v108, 16, v130
	v_and_b32_e32 v109, 0xffff0000, v130
	v_lshlrev_b32_e32 v164, 16, v131
	v_and_b32_e32 v165, 0xffff0000, v131
	v_pk_add_f32 v[128:129], v[102:103], v[106:107]
	v_pk_add_f32 v[130:131], v[100:101], v[104:105]
	v_pk_add_f32 v[108:109], v[96:97], v[108:109]
	v_mul_f32_e32 v96, v131, v131
	v_mul_f32_e32 v97, v129, v129
	v_fmac_f32_e32 v96, v130, v130
	v_fmac_f32_e32 v97, v128, v128
	v_add_f32_e32 v96, v96, v97
	v_mul_f32_e32 v97, v109, v109
	v_pk_add_f32 v[106:107], v[98:99], v[164:165]
	v_fmac_f32_e32 v97, v108, v108
	v_add_f32_e32 v96, v97, v96
	v_mul_f32_e32 v97, v107, v107
	v_fmac_f32_e32 v97, v106, v106
	v_add_f32_e32 v96, v97, v96
	v_add_f32_e32 v96, v166, v96
	ds_bpermute_b32 v97, v191, v96
	v_lshl_add_u64 v[176:177], v[152:153], 2, s[14:15]
	s_waitcnt lgkmcnt(0)
	v_add_f32_e32 v96, v96, v97
	ds_bpermute_b32 v97, v192, v96
	s_and_saveexec_b64 s[4:5], vcc
	s_cbranch_execz .LBB0_1084
	s_waitcnt lgkmcnt(0)
	v_add_f32_e32 v96, v96, v97
	v_mov_b32_e32 v237, v96
; #define UNPK4(q, lo, hi) const f32x4 lo = (f32x4){bf_lo((q).x), bf_hi((q).x), bf_lo((q).y), bf_hi((q).y)}, hi = (f32x4){bf_lo((q).z), bf_hi((q).z), bf_lo((q).w), bf_hi((q).w)}
;     __device__ __forceinline__ void operator()(f32x4 (&acc)[2][2][4][2], const Unit& u, int wr, int wc, int fr, int fq) const {
;     ...
;         for (int g = 0; g < 8; ++g) {
;             const int ai = g >> 2, m = g & 3, row = ROW_OF(ai, m); float s = 0.f;
;             if (g < 7) {
; #pragma unroll
;                 for (int bj = 0; bj < 2; ++bj) xn[bj] = *(const u32x4*)(xb + (size_t)ROW_OF((g + 1) >> 2, (g + 1) & 3) * D + col0 + bj * 128);
;             }
; #pragma unroll
;             for (int bj = 0; bj < 2; ++bj) {
;                 UNPK4(xc[bj], x0, x1);
;                 const f32x4 v0 = x0 + acc[ai][bj][m][0], v1 = x1 + acc[ai][bj][m][1];
;                 acc[ai][bj][m][0] = v0; acc[ai][bj][m][1] = v1;
;                 s += (v0[0] * v0[0] + v0[1] * v0[1]) + (v0[2] * v0[2] + v0[3] * v0[3]) + (v1[0] * v1[0] + v1[1] * v1[1]) + (v1[2] * v1[2] + v1[3] * v1[3]);
;             }
;             s += __shfl_xor(s, 16); s += __shfl_xor(s, 32);
;             if (fq == 0) __hip_atomic_fetch_add(ss + row, s, __ATOMIC_RELAXED, __HIP_MEMORY_SCOPE_AGENT);
;             if (g < 7) { xc[0] = xn[0]; xc[1] = xn[1]; }
;         }
.LBB0_1084:
	s_or_b64 exec, exec, s[4:5]
	v_add_u32_e32 v104, 48, v162
	v_ashrrev_i32_e32 v105, 31, v104
	s_waitcnt lgkmcnt(0)
	v_lshlrev_b64 v[96:97], 12, v[104:105]
	v_lshl_add_u64 v[96:97], s[74:75], 0, v[96:97]
	v_lshl_add_u64 v[96:97], v[168:169], 1, v[96:97]
	global_load_dwordx4 v[100:103], v[96:97], off
	s_nop 0
	global_load_dwordx4 v[96:99], v[96:97], off offset:256
	s_waitcnt vmcnt(3)
	v_lshlrev_b32_e32 v164, 16, v116
	v_and_b32_e32 v165, 0xffff0000, v116
	v_lshlrev_b32_e32 v116, 16, v117
	v_and_b32_e32 v117, 0xffff0000, v117
	v_lshlrev_b32_e32 v166, 16, v118
	v_and_b32_e32 v167, 0xffff0000, v118
	v_lshlrev_b32_e32 v170, 16, v119
	v_and_b32_e32 v171, 0xffff0000, v119
	v_pk_add_f32 v[94:95], v[94:95], v[116:117]
	v_pk_add_f32 v[118:119], v[92:93], v[164:165]
	v_pk_add_f32 v[116:117], v[88:89], v[166:167]
	v_mul_f32_e32 v88, v119, v119
	v_mul_f32_e32 v89, v95, v95
	v_fmac_f32_e32 v88, v118, v118
	v_fmac_f32_e32 v89, v94, v94
	v_add_f32_e32 v88, v88, v89
	v_mul_f32_e32 v89, v117, v117
	v_pk_add_f32 v[90:91], v[90:91], v[170:171]
	v_fmac_f32_e32 v89, v116, v116
	v_add_f32_e32 v88, v89, v88
	v_mul_f32_e32 v89, v91, v91
	v_fmac_f32_e32 v89, v90, v90
	v_add_f32_e32 v170, v89, v88
	s_waitcnt vmcnt(2)
	v_lshlrev_b32_e32 v88, 16, v112
	v_and_b32_e32 v89, 0xffff0000, v112
	v_lshlrev_b32_e32 v92, 16, v113
	v_and_b32_e32 v93, 0xffff0000, v113
	v_lshlrev_b32_e32 v112, 16, v114
	v_and_b32_e32 v113, 0xffff0000, v114
	v_lshlrev_b32_e32 v166, 16, v115
	v_and_b32_e32 v167, 0xffff0000, v115
	v_pk_add_f32 v[114:115], v[86:87], v[92:93]
	v_pk_add_f32 v[164:165], v[84:85], v[88:89]
	v_pk_add_f32 v[112:113], v[80:81], v[112:113]
	v_mul_f32_e32 v80, v165, v165
	v_mul_f32_e32 v81, v115, v115
	v_fmac_f32_e32 v80, v164, v164
	v_fmac_f32_e32 v81, v114, v114
	v_add_f32_e32 v80, v80, v81
	v_mul_f32_e32 v81, v113, v113
	v_pk_add_f32 v[92:93], v[82:83], v[166:167]
	v_fmac_f32_e32 v81, v112, v112
	v_add_f32_e32 v80, v81, v80
	v_mul_f32_e32 v81, v93, v93
	v_fmac_f32_e32 v81, v92, v92
	v_add_f32_e32 v80, v81, v80
	v_add_f32_e32 v80, v170, v80
	ds_bpermute_b32 v81, v191, v80
	v_lshl_add_u64 v[178:179], v[120:121], 2, s[14:15]
	s_waitcnt lgkmcnt(0)
	v_add_f32_e32 v80, v80, v81
	ds_bpermute_b32 v81, v192, v80
	s_and_saveexec_b64 s[4:5], vcc
	s_cbranch_execz .LBB0_1086
	s_waitcnt lgkmcnt(0)
	v_add_f32_e32 v80, v80, v81
	v_mov_b32_e32 v238, v80
.LBB0_1086:
	s_or_b64 exec, exec, s[4:5]
	v_add_u32_e32 v88, 0x80, v162
	v_ashrrev_i32_e32 v89, 31, v88
	s_waitcnt lgkmcnt(0)
	v_lshlrev_b64 v[80:81], 12, v[88:89]
	v_lshl_add_u64 v[80:81], s[74:75], 0, v[80:81]
	v_lshl_add_u64 v[80:81], v[168:169], 1, v[80:81]
	global_load_dwordx4 v[84:87], v[80:81], off
	s_nop 0
	global_load_dwordx4 v[80:83], v[80:81], off offset:256
	s_waitcnt vmcnt(3)
	v_lshlrev_b32_e32 v166, 16, v100
	v_and_b32_e32 v167, 0xffff0000, v100
	v_lshlrev_b32_e32 v100, 16, v101
	v_and_b32_e32 v101, 0xffff0000, v101
	v_lshlrev_b32_e32 v170, 16, v102
	v_and_b32_e32 v171, 0xffff0000, v102
	v_lshlrev_b32_e32 v172, 16, v103
	v_and_b32_e32 v173, 0xffff0000, v103
	v_pk_add_f32 v[78:79], v[78:79], v[100:101]
	v_pk_add_f32 v[102:103], v[76:77], v[166:167]
	v_pk_add_f32 v[100:101], v[72:73], v[170:171]
	v_mul_f32_e32 v72, v103, v103
	v_mul_f32_e32 v73, v79, v79
	v_fmac_f32_e32 v72, v102, v102
	v_fmac_f32_e32 v73, v78, v78
	v_add_f32_e32 v72, v72, v73
	v_mul_f32_e32 v73, v101, v101
	v_pk_add_f32 v[74:75], v[74:75], v[172:173]
	v_fmac_f32_e32 v73, v100, v100
	v_add_f32_e32 v72, v73, v72
	v_mul_f32_e32 v73, v75, v75
	v_fmac_f32_e32 v73, v74, v74
	v_add_f32_e32 v172, v73, v72
	s_waitcnt vmcnt(2)
	v_lshlrev_b32_e32 v72, 16, v96
	v_and_b32_e32 v73, 0xffff0000, v96
	v_lshlrev_b32_e32 v76, 16, v97
	v_and_b32_e32 v77, 0xffff0000, v97
	v_lshlrev_b32_e32 v96, 16, v98
	v_and_b32_e32 v97, 0xffff0000, v98
	v_lshlrev_b32_e32 v170, 16, v99
	v_and_b32_e32 v171, 0xffff0000, v99
	v_pk_add_f32 v[98:99], v[70:71], v[76:77]
	v_pk_add_f32 v[166:167], v[68:69], v[72:73]
	v_pk_add_f32 v[96:97], v[64:65], v[96:97]
	v_mul_f32_e32 v64, v167, v167
	v_mul_f32_e32 v65, v99, v99
	v_fmac_f32_e32 v64, v166, v166
	v_fmac_f32_e32 v65, v98, v98
	v_add_f32_e32 v64, v64, v65
	v_mul_f32_e32 v65, v97, v97
	v_pk_add_f32 v[76:77], v[66:67], v[170:171]
	v_fmac_f32_e32 v65, v96, v96
	v_add_f32_e32 v64, v65, v64
	v_mul_f32_e32 v65, v77, v77
	v_fmac_f32_e32 v65, v76, v76
	v_add_f32_e32 v64, v65, v64
	v_add_f32_e32 v64, v172, v64
	ds_bpermute_b32 v65, v191, v64
	v_lshl_add_u64 v[180:181], v[104:105], 2, s[14:15]
	s_waitcnt lgkmcnt(0)
	v_add_f32_e32 v64, v64, v65
	ds_bpermute_b32 v65, v192, v64
	s_and_saveexec_b64 s[4:5], vcc
	s_cbranch_execz .LBB0_1088
	s_waitcnt lgkmcnt(0)
	v_add_f32_e32 v64, v64, v65
	v_mov_b32_e32 v239, v64
; #define UNPK4(q, lo, hi) const f32x4 lo = (f32x4){bf_lo((q).x), bf_hi((q).x), bf_lo((q).y), bf_hi((q).y)}, hi = (f32x4){bf_lo((q).z), bf_hi((q).z), bf_lo((q).w), bf_hi((q).w)}
;     __device__ __forceinline__ void operator()(f32x4 (&acc)[2][2][4][2], const Unit& u, int wr, int wc, int fr, int fq) const {
;     ...
;         for (int g = 0; g < 8; ++g) {
;             const int ai = g >> 2, m = g & 3, row = ROW_OF(ai, m); float s = 0.f;
;             if (g < 7) {
; #pragma unroll
;                 for (int bj = 0; bj < 2; ++bj) xn[bj] = *(const u32x4*)(xb + (size_t)ROW_OF((g + 1) >> 2, (g + 1) & 3) * D + col0 + bj * 128);
;             }
; #pragma unroll
;             for (int bj = 0; bj < 2; ++bj) {
;                 UNPK4(xc[bj], x0, x1);
;                 const f32x4 v0 = x0 + acc[ai][bj][m][0], v1 = x1 + acc[ai][bj][m][1];
;                 acc[ai][bj][m][0] = v0; acc[ai][bj][m][1] = v1;
;                 s += (v0[0] * v0[0] + v0[1] * v0[1]) + (v0[2] * v0[2] + v0[3] * v0[3]) + (v1[0] * v1[0] + v1[1] * v1[1]) + (v1[2] * v1[2] + v1[3] * v1[3]);
;             }
;             s += __shfl_xor(s, 16); s += __shfl_xor(s, 32);
;             if (fq == 0) __hip_atomic_fetch_add(ss + row, s, __ATOMIC_RELAXED, __HIP_MEMORY_SCOPE_AGENT);
;             if (g < 7) { xc[0] = xn[0]; xc[1] = xn[1]; }
;         }
.LBB0_1088:
	s_or_b64 exec, exec, s[4:5]
	v_add_u32_e32 v72, 0x90, v162
	v_ashrrev_i32_e32 v73, 31, v72
	s_waitcnt lgkmcnt(0)
	v_lshlrev_b64 v[64:65], 12, v[72:73]
	v_lshl_add_u64 v[64:65], s[74:75], 0, v[64:65]
	v_lshl_add_u64 v[64:65], v[168:169], 1, v[64:65]
	global_load_dwordx4 v[68:71], v[64:65], off
	s_nop 0
	global_load_dwordx4 v[64:67], v[64:65], off offset:256
	s_waitcnt vmcnt(3)
	v_lshlrev_b32_e32 v170, 16, v84
	v_and_b32_e32 v171, 0xffff0000, v84
	v_lshlrev_b32_e32 v84, 16, v85
	v_and_b32_e32 v85, 0xffff0000, v85
	v_lshlrev_b32_e32 v172, 16, v86
	v_and_b32_e32 v173, 0xffff0000, v86
	v_lshlrev_b32_e32 v182, 16, v87
	v_and_b32_e32 v183, 0xffff0000, v87
	v_pk_add_f32 v[62:63], v[62:63], v[84:85]
	v_pk_add_f32 v[86:87], v[60:61], v[170:171]
	v_pk_add_f32 v[84:85], v[56:57], v[172:173]
	v_mul_f32_e32 v56, v87, v87
	v_mul_f32_e32 v57, v63, v63
	v_fmac_f32_e32 v56, v86, v86
	v_fmac_f32_e32 v57, v62, v62
	v_add_f32_e32 v56, v56, v57
	v_mul_f32_e32 v57, v85, v85
	v_pk_add_f32 v[58:59], v[58:59], v[182:183]
	v_fmac_f32_e32 v57, v84, v84
	v_add_f32_e32 v56, v57, v56
	v_mul_f32_e32 v57, v59, v59
	v_fmac_f32_e32 v57, v58, v58
	v_add_f32_e32 v182, v57, v56
	s_waitcnt vmcnt(2)
	v_lshlrev_b32_e32 v56, 16, v80
	v_and_b32_e32 v57, 0xffff0000, v80
	v_lshlrev_b32_e32 v60, 16, v81
	v_and_b32_e32 v61, 0xffff0000, v81
	v_lshlrev_b32_e32 v80, 16, v82
	v_and_b32_e32 v81, 0xffff0000, v82
	v_lshlrev_b32_e32 v172, 16, v83
	v_and_b32_e32 v173, 0xffff0000, v83
	v_pk_add_f32 v[82:83], v[54:55], v[60:61]
	v_pk_add_f32 v[170:171], v[52:53], v[56:57]
	v_pk_add_f32 v[80:81], v[48:49], v[80:81]
	v_mul_f32_e32 v48, v171, v171
	v_mul_f32_e32 v49, v83, v83
	v_fmac_f32_e32 v48, v170, v170
	v_fmac_f32_e32 v49, v82, v82
	v_add_f32_e32 v48, v48, v49
	v_mul_f32_e32 v49, v81, v81
	v_pk_add_f32 v[60:61], v[50:51], v[172:173]
	v_fmac_f32_e32 v49, v80, v80
	v_add_f32_e32 v48, v49, v48
	v_mul_f32_e32 v49, v61, v61
	v_fmac_f32_e32 v49, v60, v60
	v_add_f32_e32 v48, v49, v48
	v_add_f32_e32 v48, v182, v48
	ds_bpermute_b32 v49, v191, v48
	v_lshl_add_u64 v[182:183], v[88:89], 2, s[14:15]
	s_waitcnt lgkmcnt(0)
	v_add_f32_e32 v48, v48, v49
	ds_bpermute_b32 v49, v192, v48
	s_and_saveexec_b64 s[4:5], vcc
	s_cbranch_execz .LBB0_1090
	s_waitcnt lgkmcnt(0)
	v_add_f32_e32 v48, v48, v49
	v_mov_b32_e32 v240, v48
.LBB0_1090:
	s_or_b64 exec, exec, s[4:5]
	v_add_u32_e32 v56, 0xa0, v162
	v_ashrrev_i32_e32 v57, 31, v56
	s_waitcnt lgkmcnt(0)
	v_lshlrev_b64 v[48:49], 12, v[56:57]
	v_lshl_add_u64 v[48:49], s[74:75], 0, v[48:49]
	v_lshl_add_u64 v[48:49], v[168:169], 1, v[48:49]
	global_load_dwordx4 v[52:55], v[48:49], off
	s_nop 0
	global_load_dwordx4 v[48:51], v[48:49], off offset:256
	s_waitcnt vmcnt(3)
	v_lshlrev_b32_e32 v172, 16, v68
	v_and_b32_e32 v173, 0xffff0000, v68
	v_lshlrev_b32_e32 v68, 16, v69
	v_and_b32_e32 v69, 0xffff0000, v69
	v_lshlrev_b32_e32 v184, 16, v70
	v_and_b32_e32 v185, 0xffff0000, v70
	v_lshlrev_b32_e32 v186, 16, v71
	v_and_b32_e32 v187, 0xffff0000, v71
	v_pk_add_f32 v[46:47], v[46:47], v[68:69]
	v_pk_add_f32 v[70:71], v[44:45], v[172:173]
	v_pk_add_f32 v[68:69], v[40:41], v[184:185]
	v_mul_f32_e32 v40, v71, v71
	v_mul_f32_e32 v41, v47, v47
	v_fmac_f32_e32 v40, v70, v70
	v_fmac_f32_e32 v41, v46, v46
	v_add_f32_e32 v40, v40, v41
	v_mul_f32_e32 v41, v69, v69
	v_pk_add_f32 v[42:43], v[42:43], v[186:187]
	v_fmac_f32_e32 v41, v68, v68
	v_add_f32_e32 v40, v41, v40
	v_mul_f32_e32 v41, v43, v43
	v_fmac_f32_e32 v41, v42, v42
	v_add_f32_e32 v186, v41, v40
	s_waitcnt vmcnt(2)
	v_lshlrev_b32_e32 v40, 16, v64
	v_and_b32_e32 v41, 0xffff0000, v64
	v_lshlrev_b32_e32 v44, 16, v65
	v_and_b32_e32 v45, 0xffff0000, v65
	v_lshlrev_b32_e32 v64, 16, v66
	v_and_b32_e32 v65, 0xffff0000, v66
	v_lshlrev_b32_e32 v184, 16, v67
	v_and_b32_e32 v185, 0xffff0000, v67
	v_pk_add_f32 v[66:67], v[38:39], v[44:45]
	v_pk_add_f32 v[172:173], v[36:37], v[40:41]
	v_pk_add_f32 v[64:65], v[32:33], v[64:65]
	v_mul_f32_e32 v32, v173, v173
	v_mul_f32_e32 v33, v67, v67
	v_fmac_f32_e32 v32, v172, v172
	v_fmac_f32_e32 v33, v66, v66
	v_add_f32_e32 v32, v32, v33
	v_mul_f32_e32 v33, v65, v65
	v_pk_add_f32 v[44:45], v[34:35], v[184:185]
	v_fmac_f32_e32 v33, v64, v64
	v_add_f32_e32 v32, v33, v32
	v_mul_f32_e32 v33, v45, v45
	v_fmac_f32_e32 v33, v44, v44
	v_add_f32_e32 v32, v33, v32
	v_add_f32_e32 v32, v186, v32
	ds_bpermute_b32 v33, v191, v32
	v_lshl_add_u64 v[184:185], v[72:73], 2, s[14:15]
	s_waitcnt lgkmcnt(0)
	v_add_f32_e32 v32, v32, v33
	ds_bpermute_b32 v33, v192, v32
	s_and_saveexec_b64 s[4:5], vcc
	s_cbranch_execz .LBB0_1092
	s_waitcnt lgkmcnt(0)
	v_add_f32_e32 v32, v32, v33
	v_mov_b32_e32 v241, v32
; #define UNPK4(q, lo, hi) const f32x4 lo = (f32x4){bf_lo((q).x), bf_hi((q).x), bf_lo((q).y), bf_hi((q).y)}, hi = (f32x4){bf_lo((q).z), bf_hi((q).z), bf_lo((q).w), bf_hi((q).w)}
;     __device__ __forceinline__ void operator()(f32x4 (&acc)[2][2][4][2], const Unit& u, int wr, int wc, int fr, int fq) const {
;     ...
;         for (int g = 0; g < 8; ++g) {
;             const int ai = g >> 2, m = g & 3, row = ROW_OF(ai, m); float s = 0.f;
;             if (g < 7) {
; #pragma unroll
;                 for (int bj = 0; bj < 2; ++bj) xn[bj] = *(const u32x4*)(xb + (size_t)ROW_OF((g + 1) >> 2, (g + 1) & 3) * D + col0 + bj * 128);
;             }
; #pragma unroll
;             for (int bj = 0; bj < 2; ++bj) {
;                 UNPK4(xc[bj], x0, x1);
;                 const f32x4 v0 = x0 + acc[ai][bj][m][0], v1 = x1 + acc[ai][bj][m][1];
;                 acc[ai][bj][m][0] = v0; acc[ai][bj][m][1] = v1;
;                 s += (v0[0] * v0[0] + v0[1] * v0[1]) + (v0[2] * v0[2] + v0[3] * v0[3]) + (v1[0] * v1[0] + v1[1] * v1[1]) + (v1[2] * v1[2] + v1[3] * v1[3]);
;             }
;             s += __shfl_xor(s, 16); s += __shfl_xor(s, 32);
;             if (fq == 0) __hip_atomic_fetch_add(ss + row, s, __ATOMIC_RELAXED, __HIP_MEMORY_SCOPE_AGENT);
;             if (g < 7) { xc[0] = xn[0]; xc[1] = xn[1]; }
;         }
;         asm volatile("s_waitcnt vmcnt(0)" ::: "memory"); __builtin_amdgcn_s_barrier();
;         if (threadIdx.x == 0) {
;             __hip_atomic_fetch_add(cnt + u.pm, 1u, __ATOMIC_RELAXED, __HIP_MEMORY_SCOPE_AGENT);
;             unsigned sp = 0;
;             while (__hip_atomic_load(cnt + u.pm, __ATOMIC_RELAXED, __HIP_MEMORY_SCOPE_AGENT) < 8u) { __builtin_amdgcn_s_sleep(1); if (++sp > (1u << 22)) break; }
;         }
.LBB0_1092:
	s_or_b64 exec, exec, s[4:5]
	v_add_u32_e32 v40, 0xb0, v162
	v_ashrrev_i32_e32 v41, 31, v40
	s_waitcnt lgkmcnt(0)
	v_lshlrev_b64 v[32:33], 12, v[40:41]
	v_lshl_add_u64 v[32:33], s[74:75], 0, v[32:33]
	v_lshl_add_u64 v[32:33], v[168:169], 1, v[32:33]
	global_load_dwordx4 v[36:39], v[32:33], off
	s_nop 0
	global_load_dwordx4 v[32:35], v[32:33], off offset:256
	s_waitcnt vmcnt(3)
	v_lshlrev_b32_e32 v186, 16, v52
	v_and_b32_e32 v187, 0xffff0000, v52
	v_lshlrev_b32_e32 v52, 16, v53
	v_and_b32_e32 v53, 0xffff0000, v53
	v_pk_add_f32 v[30:31], v[30:31], v[52:53]
	v_pk_add_f32 v[28:29], v[28:29], v[186:187]
	v_lshlrev_b32_e32 v198, 16, v54
	v_and_b32_e32 v199, 0xffff0000, v54
	v_mul_f32_e32 v52, v29, v29
	v_mul_f32_e32 v53, v31, v31
	v_pk_add_f32 v[24:25], v[24:25], v[198:199]
	v_fmac_f32_e32 v52, v28, v28
	v_fmac_f32_e32 v53, v30, v30
	v_lshlrev_b32_e32 v54, 16, v55
	v_and_b32_e32 v55, 0xffff0000, v55
	v_add_f32_e32 v52, v52, v53
	v_mul_f32_e32 v53, v25, v25
	v_pk_add_f32 v[26:27], v[26:27], v[54:55]
	v_fmac_f32_e32 v53, v24, v24
	v_add_f32_e32 v52, v53, v52
	v_mul_f32_e32 v53, v27, v27
	v_fmac_f32_e32 v53, v26, v26
	v_add_f32_e32 v198, v53, v52
	s_waitcnt vmcnt(2)
	v_lshlrev_b32_e32 v52, 16, v48
	v_and_b32_e32 v53, 0xffff0000, v48
	v_lshlrev_b32_e32 v48, 16, v49
	v_and_b32_e32 v49, 0xffff0000, v49
	v_lshlrev_b32_e32 v54, 16, v50
	v_and_b32_e32 v55, 0xffff0000, v50
	v_lshlrev_b32_e32 v186, 16, v51
	v_and_b32_e32 v187, 0xffff0000, v51
	v_pk_add_f32 v[48:49], v[22:23], v[48:49]
	v_pk_add_f32 v[50:51], v[20:21], v[52:53]
	v_mul_f32_e32 v21, v49, v49
	v_mul_f32_e32 v20, v51, v51
	v_pk_add_f32 v[16:17], v[16:17], v[54:55]
	v_fmac_f32_e32 v20, v50, v50
	v_fmac_f32_e32 v21, v48, v48
	v_add_f32_e32 v20, v20, v21
	v_mul_f32_e32 v21, v17, v17
	v_pk_add_f32 v[18:19], v[18:19], v[186:187]
	v_fmac_f32_e32 v21, v16, v16
	v_add_f32_e32 v20, v21, v20
	v_mul_f32_e32 v21, v19, v19
	v_fmac_f32_e32 v21, v18, v18
	v_add_f32_e32 v20, v21, v20
	v_add_f32_e32 v20, v198, v20
	ds_bpermute_b32 v21, v191, v20
	v_lshl_add_u64 v[186:187], v[56:57], 2, s[14:15]
	s_waitcnt lgkmcnt(0)
	v_add_f32_e32 v20, v20, v21
	ds_bpermute_b32 v21, v192, v20
	s_and_saveexec_b64 s[4:5], vcc
	s_cbranch_execz .LBB0_1094
	s_waitcnt lgkmcnt(0)
	v_add_f32_e32 v20, v20, v21
	v_mov_b32_e32 v242, v20
.LBB0_1094:
	s_or_b64 exec, exec, s[4:5]
	s_waitcnt vmcnt(1)
	v_lshlrev_b32_e32 v20, 16, v36
	s_waitcnt lgkmcnt(0)
	v_and_b32_e32 v21, 0xffff0000, v36
	v_lshlrev_b32_e32 v22, 16, v37
	v_and_b32_e32 v23, 0xffff0000, v37
	v_lshlrev_b32_e32 v36, 16, v38
	v_and_b32_e32 v37, 0xffff0000, v38
	v_lshlrev_b32_e32 v52, 16, v39
	v_and_b32_e32 v53, 0xffff0000, v39
	v_pk_add_f32 v[22:23], v[14:15], v[22:23]
	v_pk_add_f32 v[38:39], v[12:13], v[20:21]
	v_pk_add_f32 v[36:37], v[8:9], v[36:37]
	v_mul_f32_e32 v8, v39, v39
	v_mul_f32_e32 v9, v23, v23
	v_fmac_f32_e32 v8, v38, v38
	v_fmac_f32_e32 v9, v22, v22
	v_add_f32_e32 v8, v8, v9
	v_mul_f32_e32 v9, v37, v37
	v_pk_add_f32 v[20:21], v[10:11], v[52:53]
	v_fmac_f32_e32 v9, v36, v36
	v_add_f32_e32 v8, v9, v8
	v_mul_f32_e32 v9, v21, v21
	v_fmac_f32_e32 v9, v20, v20
	v_add_f32_e32 v198, v9, v8
	s_waitcnt vmcnt(0)
	v_lshlrev_b32_e32 v8, 16, v32
	v_and_b32_e32 v9, 0xffff0000, v32
	v_lshlrev_b32_e32 v10, 16, v33
	v_and_b32_e32 v11, 0xffff0000, v33
	v_lshlrev_b32_e32 v12, 16, v34
	v_and_b32_e32 v13, 0xffff0000, v34
	v_lshlrev_b32_e32 v14, 16, v35
	v_and_b32_e32 v15, 0xffff0000, v35
	v_pk_add_f32 v[34:35], v[6:7], v[10:11]
	v_pk_add_f32 v[54:55], v[4:5], v[8:9]
	v_pk_add_f32 v[52:53], v[0:1], v[12:13]
	v_mul_f32_e32 v0, v55, v55
	v_mul_f32_e32 v1, v35, v35
	v_fmac_f32_e32 v0, v54, v54
	v_fmac_f32_e32 v1, v34, v34
	v_add_f32_e32 v0, v0, v1
	v_mul_f32_e32 v1, v53, v53
	v_pk_add_f32 v[32:33], v[2:3], v[14:15]
	v_fmac_f32_e32 v1, v52, v52
	v_add_f32_e32 v0, v1, v0
	v_mul_f32_e32 v1, v33, v33
	v_fmac_f32_e32 v1, v32, v32
	v_add_f32_e32 v0, v1, v0
	v_add_f32_e32 v0, v198, v0
	ds_bpermute_b32 v1, v191, v0
	s_waitcnt lgkmcnt(0)
	v_add_f32_e32 v2, v0, v1
	ds_bpermute_b32 v3, v192, v2
	v_lshl_add_u64 v[0:1], v[40:41], 2, s[14:15]
	s_and_saveexec_b64 s[4:5], vcc
	s_cbranch_execz .LBB0_1096
	s_waitcnt lgkmcnt(0)
	v_add_f32_e32 v2, v2, v3
	global_atomic_add_f32 v[0:1], v2, off
	global_atomic_add_f32 v[174:175], v236, off
	global_atomic_add_f32 v[176:177], v237, off
	global_atomic_add_f32 v[178:179], v238, off
	global_atomic_add_f32 v[180:181], v239, off
	global_atomic_add_f32 v[182:183], v240, off
	global_atomic_add_f32 v[184:185], v241, off
	global_atomic_add_f32 v[186:187], v242, off
